# RG-LRU backward loop: gate biases of the first three column groups pre-multiplied by -log2(e) (already loaded at loop entry), bias add + scale fused into one fma
# baseline (speedup 1.0000x reference)
; #define LAS __attribute__((address_space(3)))
; __device__ __forceinline__ float bf2f(bf16_t b) { return __uint_as_float(((unsigned)b) << 16); }
; __device__ __forceinline__ float sigmoidf_(float x) { return __builtin_amdgcn_rcpf(1.0f + __expf(-x)); }
; __device__ __forceinline__ f32x4 mfma16(bf16x8 a, bf16x8 b, f32x4 c) { return __builtin_amdgcn_mfma_f32_16x16x32_bf16(a, b, c, 0, 0, 0); }
; template <int DIR> __device__ __forceinline__ void lru_dir(const Params& p, int l, int n, int h, int lane, LAS bf16_t* XC, LAS float* STA, LAS float* STU) {
;     ...
;         for (int ks = 0; ks < 2; ++ks) xf[ks] = *(const LAS bf16x8*)(XC + (16 * mi + c) * 520 + 64 * h + 32 * ks + 8 * q);
;         f32x4 za[4], zx[4];
; #pragma unroll
;         for (int nf = 0; nf < 4; ++nf) { za[nf] = (f32x4){0.f, 0.f, 0.f, 0.f}; zx[nf] = za[nf];
;             za[nf] = mfma16(wa[nf][0], xf[0], za[nf]); za[nf] = mfma16(wa[nf][1], xf[1], za[nf]);
;             zx[nf] = mfma16(wx[nf][0], xf[0], zx[nf]); zx[nf] = mfma16(wx[nf][1], xf[1], zx[nf]); }
; #pragma unroll
;         for (int nf = 0; nf < 4; ++nf) {
;             const int jo = 16 * nf + 4 * q;
;             const bf16x4 xc4 = *(const LAS bf16x4*)(XC + (16 * mi + c) * 520 + 64 * h + jo);
;             const f32x4 zav = za[nf] + ba4[nf], zxv = zx[nf] + bx4[nf];
;             f32x4 av, uv;
; #pragma unroll
;             for (int r = 0; r < 4; ++r) {
;                 const float ra = sigmoidf_(zav[r]), ix = sigmoidf_(zxv[r]);
;                 const float la = ra * sp4[nf][r];
;                 av[r] = __expf(la);
;                 const float x2 = 2.0f * la;
;                 const float om = -x2 * (1.0f + x2 * (0.5f + x2 * (0.16666667f + x2 * (0.041666668f + x2 * (0.0083333338f + x2 * (0.0013888889f + x2 * 0.0001984127f))))));
;                 uv[r] = bf2f((bf16_t)xc4[r]) * ix * __builtin_amdgcn_sqrtf(fmaxf(om, 0.f));
;             }
;             *(LAS f32x4*)(STA + c * 68 + jo) = av; *(LAS f32x4*)(STU + c * 68 + jo) = uv;
;         }
;         LDS_FENCE();
;         float aa[16], uu[16];
; #pragma unroll
;         for (int s = 0; s < 16; ++s) { aa[s] = STA[s * 68 + j]; uu[s] = STU[s * 68 + j]; }
;         LDS_FENCE();
; #pragma unroll
;         for (int s = 0; s < 16; ++s) {
;             const int tl = DIR == 0 ? s : 15 - s;
;             hcar = aa[tl] * hcar + uu[tl]; P *= aa[tl];
.Llru0_loop:
	ds_read_b128 v[172:175], v150
	ds_read_b128 v[178:181], v150 offset:64
	ds_read_b64 v[182:183], v151
	ds_read_b64 v[184:185], v151 offset:32
	ds_read_b64 v[186:187], v151 offset:64
	ds_read_b64 v[188:189], v151 offset:96
	s_add_u32 s64, s66, s0
	s_addc_u32 s65, s67, 0
	s_waitcnt lgkmcnt(4)
	v_mfma_f32_16x16x32_bf16 v[156:159], v[4:7], v[172:175], 0
	v_mfma_f32_16x16x32_bf16 v[96:99], v[0:3], v[172:175], 0
	v_mfma_f32_16x16x32_bf16 v[160:163], v[24:27], v[172:175], 0
	v_mfma_f32_16x16x32_bf16 v[100:103], v[32:35], v[172:175], 0
	v_mfma_f32_16x16x32_bf16 v[164:167], v[48:51], v[172:175], 0
	v_mfma_f32_16x16x32_bf16 v[104:107], v[56:59], v[172:175], 0
	v_mfma_f32_16x16x32_bf16 v[168:171], v[72:75], v[172:175], 0
	v_mfma_f32_16x16x32_bf16 v[108:111], v[80:83], v[172:175], 0
	v_mfma_f32_16x16x32_bf16 v[156:159], v[8:11], v[178:181], v[156:159]
	v_mfma_f32_16x16x32_bf16 v[96:99], v[12:15], v[178:181], v[96:99]
	v_mfma_f32_16x16x32_bf16 v[160:163], v[28:31], v[178:181], v[160:163]
	v_mfma_f32_16x16x32_bf16 v[100:103], v[36:39], v[178:181], v[100:103]
	v_mfma_f32_16x16x32_bf16 v[164:167], v[52:55], v[178:181], v[164:167]
	v_mfma_f32_16x16x32_bf16 v[104:107], v[60:63], v[178:181], v[104:107]
	v_mfma_f32_16x16x32_bf16 v[168:171], v[76:79], v[178:181], v[168:171]
	v_mfma_f32_16x16x32_bf16 v[108:111], v[84:87], v[178:181], v[108:111]
	s_waitcnt lgkmcnt(0)
	v_lshlrev_b32_e32 v204, 16, v182
	v_and_b32_e32 v205, 0xffff0000, v182
	v_lshlrev_b32_e32 v206, 16, v183
	v_and_b32_e32 v207, 0xffff0000, v183
	v_lshlrev_b32_e32 v208, 16, v184
	v_and_b32_e32 v209, 0xffff0000, v184
	v_lshlrev_b32_e32 v210, 16, v185
	v_and_b32_e32 v211, 0xffff0000, v185
	v_lshlrev_b32_e32 v212, 16, v186
	v_and_b32_e32 v213, 0xffff0000, v186
	v_lshlrev_b32_e32 v214, 16, v187
	v_and_b32_e32 v215, 0xffff0000, v187
	v_lshlrev_b32_e32 v216, 16, v188
	v_and_b32_e32 v217, 0xffff0000, v188
	v_lshlrev_b32_e32 v218, 16, v189
	v_and_b32_e32 v219, 0xffff0000, v189
	v_fmamk_f32 v192, v156, 0xbfb8aa3b, v16
	v_fmamk_f32 v195, v157, 0xbfb8aa3b, v17
	v_fmamk_f32 v198, v158, 0xbfb8aa3b, v18
	v_fmamk_f32 v201, v159, 0xbfb8aa3b, v19
	v_fmamk_f32 v193, v96, 0xbfb8aa3b, v20
	v_fmamk_f32 v196, v97, 0xbfb8aa3b, v21
	v_fmamk_f32 v199, v98, 0xbfb8aa3b, v22
	v_fmamk_f32 v202, v99, 0xbfb8aa3b, v23
	v_exp_f32_e32 v192, v192
	v_exp_f32_e32 v195, v195
	v_exp_f32_e32 v198, v198
	v_exp_f32_e32 v201, v201
	v_exp_f32_e32 v193, v193
	v_exp_f32_e32 v196, v196
	v_exp_f32_e32 v199, v199
	v_exp_f32_e32 v202, v202
	v_add_f32_e32 v192, 1.0, v192
	v_add_f32_e32 v195, 1.0, v195
	v_add_f32_e32 v198, 1.0, v198
	v_add_f32_e32 v201, 1.0, v201
	v_add_f32_e32 v193, 1.0, v193
	v_add_f32_e32 v196, 1.0, v196
	v_add_f32_e32 v199, 1.0, v199
	v_add_f32_e32 v202, 1.0, v202
	v_rcp_f32_e32 v192, v192
	v_rcp_f32_e32 v195, v195
	v_rcp_f32_e32 v198, v198
	v_rcp_f32_e32 v201, v201
	v_rcp_f32_e32 v193, v193
	v_rcp_f32_e32 v196, v196
	v_rcp_f32_e32 v199, v199
	v_rcp_f32_e32 v202, v202
	v_mul_f32_e32 v192, v148, v192
	v_mul_f32_e32 v195, v147, v195
	v_mul_f32_e32 v198, v146, v198
	v_mul_f32_e32 v201, v145, v201
	v_exp_f32_e32 v156, v192
	v_exp_f32_e32 v157, v195
	v_exp_f32_e32 v158, v198
	v_exp_f32_e32 v159, v201
	v_fma_f32 v192, -v156, v156, 1.0
	v_fma_f32 v195, -v157, v157, 1.0
	v_fma_f32 v198, -v158, v158, 1.0
	v_fma_f32 v201, -v159, v159, 1.0
	v_max_f32_e32 v192, 0, v192
	v_max_f32_e32 v195, 0, v195
	v_max_f32_e32 v198, 0, v198
	v_max_f32_e32 v201, 0, v201
	v_sqrt_f32_e32 v192, v192
	v_sqrt_f32_e32 v195, v195
	v_sqrt_f32_e32 v198, v198
	v_sqrt_f32_e32 v201, v201
	v_mul_f32_e32 v193, v193, v204
	v_mul_f32_e32 v196, v196, v205
	v_mul_f32_e32 v199, v199, v206
	v_mul_f32_e32 v202, v202, v207
	v_mul_f32_e32 v96, v193, v192
	v_mul_f32_e32 v97, v196, v195
	v_mul_f32_e32 v98, v199, v198
	v_mul_f32_e32 v99, v202, v201
	ds_write_b128 v154, v[156:159]
	ds_write_b128 v154, v[96:99] offset:4352
	v_fmamk_f32 v192, v160, 0xbfb8aa3b, v40
	v_fmamk_f32 v195, v161, 0xbfb8aa3b, v41
	v_fmamk_f32 v198, v162, 0xbfb8aa3b, v42
	v_fmamk_f32 v201, v163, 0xbfb8aa3b, v43
	v_fmamk_f32 v193, v100, 0xbfb8aa3b, v44
	v_fmamk_f32 v196, v101, 0xbfb8aa3b, v45
	v_fmamk_f32 v199, v102, 0xbfb8aa3b, v46
	v_fmamk_f32 v202, v103, 0xbfb8aa3b, v47
	v_exp_f32_e32 v192, v192
	v_exp_f32_e32 v195, v195
	v_exp_f32_e32 v198, v198
	v_exp_f32_e32 v201, v201
	v_exp_f32_e32 v193, v193
	v_exp_f32_e32 v196, v196
	v_exp_f32_e32 v199, v199
	v_exp_f32_e32 v202, v202
	v_add_f32_e32 v192, 1.0, v192
	v_add_f32_e32 v195, 1.0, v195
	v_add_f32_e32 v198, 1.0, v198
	v_add_f32_e32 v201, 1.0, v201
	v_add_f32_e32 v193, 1.0, v193
	v_add_f32_e32 v196, 1.0, v196
	v_add_f32_e32 v199, 1.0, v199
	v_add_f32_e32 v202, 1.0, v202
	v_rcp_f32_e32 v192, v192
	v_rcp_f32_e32 v195, v195
	v_rcp_f32_e32 v198, v198
	v_rcp_f32_e32 v201, v201
	v_rcp_f32_e32 v193, v193
	v_rcp_f32_e32 v196, v196
	v_rcp_f32_e32 v199, v199
	v_rcp_f32_e32 v202, v202
	v_mul_f32_e32 v192, v144, v192
	v_mul_f32_e32 v195, v143, v195
	v_mul_f32_e32 v198, v142, v198
	v_mul_f32_e32 v201, v141, v201
	v_exp_f32_e32 v160, v192
	v_exp_f32_e32 v161, v195
	v_exp_f32_e32 v162, v198
	v_exp_f32_e32 v163, v201
	v_fma_f32 v192, -v160, v160, 1.0
	v_fma_f32 v195, -v161, v161, 1.0
	v_fma_f32 v198, -v162, v162, 1.0
	v_fma_f32 v201, -v163, v163, 1.0
	v_max_f32_e32 v192, 0, v192
	v_max_f32_e32 v195, 0, v195
	v_max_f32_e32 v198, 0, v198
	v_max_f32_e32 v201, 0, v201
	v_sqrt_f32_e32 v192, v192
	v_sqrt_f32_e32 v195, v195
	v_sqrt_f32_e32 v198, v198
	v_sqrt_f32_e32 v201, v201
	v_mul_f32_e32 v193, v193, v208
	v_mul_f32_e32 v196, v196, v209
	v_mul_f32_e32 v199, v199, v210
	v_mul_f32_e32 v202, v202, v211
	v_mul_f32_e32 v100, v193, v192
	v_mul_f32_e32 v101, v196, v195
; #define LAS __attribute__((address_space(3)))
; __device__ __forceinline__ float bf2f(bf16_t b) { return __uint_as_float(((unsigned)b) << 16); }
; __device__ __forceinline__ unsigned cvtpk(float lo, float hi) { const f32x2 v = (f32x2){lo, hi}; const bf16v2 b = __builtin_convertvector(v, bf16v2); return __builtin_bit_cast(unsigned, b); }
; __device__ __forceinline__ float sigmoidf_(float x) { return __builtin_amdgcn_rcpf(1.0f + __expf(-x)); }
; #define LDS_FENCE() asm volatile("s_waitcnt lgkmcnt(0)" ::: "memory")
; template <int DIR> __device__ __forceinline__ void lru_dir(const Params& p, int l, int n, int h, int lane, LAS bf16_t* XC, LAS float* STA, LAS float* STU) {
;     ...
;         for (int nf = 0; nf < 4; ++nf) {
;             const int jo = 16 * nf + 4 * q;
;             const bf16x4 xc4 = *(const LAS bf16x4*)(XC + (16 * mi + c) * 520 + 64 * h + jo);
;             const f32x4 zav = za[nf] + ba4[nf], zxv = zx[nf] + bx4[nf];
;             f32x4 av, uv;
; #pragma unroll
;             for (int r = 0; r < 4; ++r) {
;                 const float ra = sigmoidf_(zav[r]), ix = sigmoidf_(zxv[r]);
;                 const float la = ra * sp4[nf][r];
;                 av[r] = __expf(la);
;                 const float x2 = 2.0f * la;
;                 const float om = -x2 * (1.0f + x2 * (0.5f + x2 * (0.16666667f + x2 * (0.041666668f + x2 * (0.0083333338f + x2 * (0.0013888889f + x2 * 0.0001984127f))))));
;                 uv[r] = bf2f((bf16_t)xc4[r]) * ix * __builtin_amdgcn_sqrtf(fmaxf(om, 0.f));
;             }
;             *(LAS f32x4*)(STA + c * 68 + jo) = av; *(LAS f32x4*)(STU + c * 68 + jo) = uv;
;         }
;         LDS_FENCE();
;         float aa[16], uu[16];
; #pragma unroll
;         for (int s = 0; s < 16; ++s) { aa[s] = STA[s * 68 + j]; uu[s] = STU[s * 68 + j]; }
;         LDS_FENCE();
; #pragma unroll
;         for (int s = 0; s < 16; ++s) {
;             const int tl = DIR == 0 ? s : 15 - s;
;             hcar = aa[tl] * hcar + uu[tl]; P *= aa[tl];
;             const size_t row = (size_t)(t0 + 16 * mi + tl);
;             if (DIR == 0) { const unsigned w = cvtpk(hcar, P); y[row * D + 64 * h + j] = (bf16_t)(w & 0xffffu); y[row * D + 512 + 64 * h + j] = (bf16_t)(w >> 16); }
	v_mul_f32_e32 v102, v199, v198
	v_mul_f32_e32 v103, v202, v201
	ds_write_b128 v154, v[160:163] offset:64
	ds_write_b128 v154, v[100:103] offset:4416
	v_fmamk_f32 v192, v164, 0xbfb8aa3b, v64
	v_fmamk_f32 v195, v165, 0xbfb8aa3b, v65
	v_fmamk_f32 v198, v166, 0xbfb8aa3b, v66
	v_fmamk_f32 v201, v167, 0xbfb8aa3b, v67
	v_fmamk_f32 v193, v104, 0xbfb8aa3b, v68
	v_fmamk_f32 v196, v105, 0xbfb8aa3b, v69
	v_fmamk_f32 v199, v106, 0xbfb8aa3b, v70
	v_fmamk_f32 v202, v107, 0xbfb8aa3b, v71
	v_exp_f32_e32 v192, v192
	v_exp_f32_e32 v195, v195
	v_exp_f32_e32 v198, v198
	v_exp_f32_e32 v201, v201
	v_exp_f32_e32 v193, v193
	v_exp_f32_e32 v196, v196
	v_exp_f32_e32 v199, v199
	v_exp_f32_e32 v202, v202
	v_add_f32_e32 v192, 1.0, v192
	v_add_f32_e32 v195, 1.0, v195
	v_add_f32_e32 v198, 1.0, v198
	v_add_f32_e32 v201, 1.0, v201
	v_add_f32_e32 v193, 1.0, v193
	v_add_f32_e32 v196, 1.0, v196
	v_add_f32_e32 v199, 1.0, v199
	v_add_f32_e32 v202, 1.0, v202
	v_rcp_f32_e32 v192, v192
	v_rcp_f32_e32 v195, v195
	v_rcp_f32_e32 v198, v198
	v_rcp_f32_e32 v201, v201
	v_rcp_f32_e32 v193, v193
	v_rcp_f32_e32 v196, v196
	v_rcp_f32_e32 v199, v199
	v_rcp_f32_e32 v202, v202
	v_mul_f32_e32 v192, v140, v192
	v_mul_f32_e32 v195, v139, v195
	v_mul_f32_e32 v198, v138, v198
	v_mul_f32_e32 v201, v137, v201
	v_exp_f32_e32 v164, v192
	v_exp_f32_e32 v165, v195
	v_exp_f32_e32 v166, v198
	v_exp_f32_e32 v167, v201
	v_fma_f32 v192, -v164, v164, 1.0
	v_fma_f32 v195, -v165, v165, 1.0
	v_fma_f32 v198, -v166, v166, 1.0
	v_fma_f32 v201, -v167, v167, 1.0
	v_max_f32_e32 v192, 0, v192
	v_max_f32_e32 v195, 0, v195
	v_max_f32_e32 v198, 0, v198
	v_max_f32_e32 v201, 0, v201
	v_sqrt_f32_e32 v192, v192
	v_sqrt_f32_e32 v195, v195
	v_sqrt_f32_e32 v198, v198
	v_sqrt_f32_e32 v201, v201
	v_mul_f32_e32 v193, v193, v212
	v_mul_f32_e32 v196, v196, v213
	v_mul_f32_e32 v199, v199, v214
	v_mul_f32_e32 v202, v202, v215
	v_mul_f32_e32 v104, v193, v192
	v_mul_f32_e32 v105, v196, v195
	v_mul_f32_e32 v106, v199, v198
	v_mul_f32_e32 v107, v202, v201
	ds_write_b128 v154, v[164:167] offset:128
	ds_write_b128 v154, v[104:107] offset:4480
	v_fmamk_f32 v192, v168, 0xbfb8aa3b, v88
	v_fmamk_f32 v195, v169, 0xbfb8aa3b, v89
	v_fmamk_f32 v198, v170, 0xbfb8aa3b, v90
	v_fmamk_f32 v201, v171, 0xbfb8aa3b, v91
	v_fmamk_f32 v193, v108, 0xbfb8aa3b, v92
	v_fmamk_f32 v196, v109, 0xbfb8aa3b, v93
	v_fmamk_f32 v199, v110, 0xbfb8aa3b, v94
	v_fmamk_f32 v202, v111, 0xbfb8aa3b, v95
	v_exp_f32_e32 v192, v192
	v_exp_f32_e32 v195, v195
	v_exp_f32_e32 v198, v198
	v_exp_f32_e32 v201, v201
	v_exp_f32_e32 v193, v193
	v_exp_f32_e32 v196, v196
	v_exp_f32_e32 v199, v199
	v_exp_f32_e32 v202, v202
	v_add_f32_e32 v192, 1.0, v192
	v_add_f32_e32 v195, 1.0, v195
	v_add_f32_e32 v198, 1.0, v198
	v_add_f32_e32 v201, 1.0, v201
	v_add_f32_e32 v193, 1.0, v193
	v_add_f32_e32 v196, 1.0, v196
	v_add_f32_e32 v199, 1.0, v199
	v_add_f32_e32 v202, 1.0, v202
	v_rcp_f32_e32 v192, v192
	v_rcp_f32_e32 v195, v195
	v_rcp_f32_e32 v198, v198
	v_rcp_f32_e32 v201, v201
	v_rcp_f32_e32 v193, v193
	v_rcp_f32_e32 v196, v196
	v_rcp_f32_e32 v199, v199
	v_rcp_f32_e32 v202, v202
	v_mul_f32_e32 v192, v136, v192
	v_mul_f32_e32 v195, v135, v195
	v_mul_f32_e32 v198, v134, v198
	v_mul_f32_e32 v201, v149, v201
	v_exp_f32_e32 v168, v192
	v_exp_f32_e32 v169, v195
	v_exp_f32_e32 v170, v198
	v_exp_f32_e32 v171, v201
	v_fma_f32 v192, -v168, v168, 1.0
	v_fma_f32 v195, -v169, v169, 1.0
	v_fma_f32 v198, -v170, v170, 1.0
	v_fma_f32 v201, -v171, v171, 1.0
	v_max_f32_e32 v192, 0, v192
	v_max_f32_e32 v195, 0, v195
	v_max_f32_e32 v198, 0, v198
	v_max_f32_e32 v201, 0, v201
	v_sqrt_f32_e32 v192, v192
	v_sqrt_f32_e32 v195, v195
	v_sqrt_f32_e32 v198, v198
	v_sqrt_f32_e32 v201, v201
	v_mul_f32_e32 v193, v193, v216
	v_mul_f32_e32 v196, v196, v217
	v_mul_f32_e32 v199, v199, v218
	v_mul_f32_e32 v202, v202, v219
	v_mul_f32_e32 v108, v193, v192
	v_mul_f32_e32 v109, v196, v195
	v_mul_f32_e32 v110, v199, v198
	v_mul_f32_e32 v111, v202, v201
	ds_write_b128 v154, v[168:171] offset:192
	ds_write_b128 v154, v[108:111] offset:4544
	s_waitcnt lgkmcnt(0)
	ds_read_b32 v204, v155
	ds_read_b32 v172, v155 offset:4352
	ds_read_b32 v205, v155 offset:272
	ds_read_b32 v173, v155 offset:4624
	ds_read_b32 v206, v155 offset:544
	ds_read_b32 v174, v155 offset:4896
	ds_read_b32 v207, v155 offset:816
	ds_read_b32 v175, v155 offset:5168
	ds_read_b32 v208, v155 offset:1088
	ds_read_b32 v178, v155 offset:5440
	ds_read_b32 v209, v155 offset:1360
	ds_read_b32 v179, v155 offset:5712
	ds_read_b32 v210, v155 offset:1632
	ds_read_b32 v180, v155 offset:5984
	ds_read_b32 v211, v155 offset:1904
	ds_read_b32 v181, v155 offset:6256
	s_waitcnt lgkmcnt(14)
	v_fma_f32 v130, v130, v204, v172
	v_mul_f32_e32 v129, v129, v204
	v_cvt_pk_bf16_f32 v190, v130, v129
	global_store_short v220, v190, s[64:65] offset:-4096
	global_store_short_d16_hi v220, v190, s[64:65] offset:-3072
	ds_read_b32 v212, v155 offset:2176
	ds_read_b32 v182, v155 offset:6528
	s_waitcnt lgkmcnt(14)
	v_fma_f32 v130, v130, v205, v173
	v_mul_f32_e32 v129, v129, v205
	v_cvt_pk_bf16_f32 v191, v130, v129
	global_store_short v220, v191, s[64:65] offset:-2048
	global_store_short_d16_hi v220, v191, s[64:65] offset:-1024
	ds_read_b32 v213, v155 offset:2448
	ds_read_b32 v183, v155 offset:6800
	s_waitcnt lgkmcnt(14)
	v_fma_f32 v130, v130, v206, v174
	v_mul_f32_e32 v129, v129, v206
	v_cvt_pk_bf16_f32 v190, v130, v129
	global_store_short v220, v190, s[64:65] offset:0
	global_store_short_d16_hi v220, v190, s[64:65] offset:1024
	ds_read_b32 v214, v155 offset:2720
	ds_read_b32 v184, v155 offset:7072
	s_waitcnt lgkmcnt(14)
; __device__ __forceinline__ float bf2f(bf16_t b) { return __uint_as_float(((unsigned)b) << 16); }
; __device__ __forceinline__ unsigned cvtpk(float lo, float hi) { const f32x2 v = (f32x2){lo, hi}; const bf16v2 b = __builtin_convertvector(v, bf16v2); return __builtin_bit_cast(unsigned, b); }
; template <int DIR> __device__ __forceinline__ void lru_dir(const Params& p, int l, int n, int h, int lane, LAS bf16_t* XC, LAS float* STA, LAS float* STU) {
;     ...
;     const bf16_t* LWa = LW + ((size_t)(DIR * 2 + 0) * 8 + h) * 4096 + c * 64 + 8 * q; const bf16_t* LWx = LW + ((size_t)(DIR * 2 + 1) * 8 + h) * 4096 + c * 64 + 8 * q;
;     bf16x8 wa[4][2], wx[4][2]; f32x4 sp4[4], ba4[4], bx4[4];
; #pragma unroll
;     for (int nf = 0; nf < 4; ++nf) {
; #pragma unroll
;         for (int ks = 0; ks < 2; ++ks) { wa[nf][ks] = *(const bf16x8*)(LWa + nf * 1024 + 32 * ks); wx[nf][ks] = *(const bf16x8*)(LWx + nf * 1024 + 32 * ks); }
;         const f32x4 lam4 = *(const f32x4*)(lam + 16 * nf + 4 * q); ba4[nf] = *(const f32x4*)(b_a + 16 * nf + 4 * q); bx4[nf] = *(const f32x4*)(b_x + 16 * nf + 4 * q);
;     ...
;         for (int s = 0; s < 16; ++s) {
;             const int tl = DIR == 0 ? s : 15 - s;
;             hcar = aa[tl] * hcar + uu[tl]; P *= aa[tl];
;             const size_t row = (size_t)(t0 + 16 * mi + tl);
;             if (DIR == 0) { const unsigned w = cvtpk(hcar, P); y[row * D + 64 * h + j] = (bf16_t)(w & 0xffffu); y[row * D + 512 + 64 * h + j] = (bf16_t)(w >> 16); }
;             else { const unsigned w = cvtpk(bf2f(hfp[tl]) + hcar, P); y[row * D + 64 * h + j] = (bf16_t)(w & 0xffffu); __builtin_nontemporal_store((bf16_t)(w >> 16), PB + row * 512 + 64 * h + j); }
;         }
;     }
;     Aprod[(size_t)(DIR * NCH + n) * 512 + 64 * h + j] = P; Hend[(size_t)(DIR * NCH + n) * 512 + 64 * h + j] = hcar;
	v_fma_f32 v130, v130, v207, v175
	v_mul_f32_e32 v129, v129, v207
	v_cvt_pk_bf16_f32 v191, v130, v129
	global_store_short v220, v191, s[64:65] offset:2048
	global_store_short_d16_hi v220, v191, s[64:65] offset:3072
	ds_read_b32 v215, v155 offset:2992
	ds_read_b32 v185, v155 offset:7344
	s_waitcnt lgkmcnt(14)
	v_fma_f32 v130, v130, v208, v178
	v_mul_f32_e32 v129, v129, v208
	v_cvt_pk_bf16_f32 v190, v130, v129
	s_add_u32 s64, s64, 0x2000
	s_addc_u32 s65, s65, 0
	global_store_short v220, v190, s[64:65] offset:-4096
	global_store_short_d16_hi v220, v190, s[64:65] offset:-3072
	ds_read_b32 v216, v155 offset:3264
	ds_read_b32 v186, v155 offset:7616
	s_waitcnt lgkmcnt(14)
	v_fma_f32 v130, v130, v209, v179
	v_mul_f32_e32 v129, v129, v209
	v_cvt_pk_bf16_f32 v191, v130, v129
	global_store_short v220, v191, s[64:65] offset:-2048
	global_store_short_d16_hi v220, v191, s[64:65] offset:-1024
	ds_read_b32 v217, v155 offset:3536
	ds_read_b32 v187, v155 offset:7888
	s_waitcnt lgkmcnt(14)
	v_fma_f32 v130, v130, v210, v180
	v_mul_f32_e32 v129, v129, v210
	v_cvt_pk_bf16_f32 v190, v130, v129
	global_store_short v220, v190, s[64:65] offset:0
	global_store_short_d16_hi v220, v190, s[64:65] offset:1024
	ds_read_b32 v218, v155 offset:3808
	ds_read_b32 v188, v155 offset:8160
	s_waitcnt lgkmcnt(14)
	v_fma_f32 v130, v130, v211, v181
	v_mul_f32_e32 v129, v129, v211
	v_cvt_pk_bf16_f32 v191, v130, v129
	global_store_short v220, v191, s[64:65] offset:2048
	global_store_short_d16_hi v220, v191, s[64:65] offset:3072
	ds_read_b32 v219, v155 offset:4080
	ds_read_b32 v189, v155 offset:8432
	s_waitcnt lgkmcnt(14)
	v_fma_f32 v130, v130, v212, v182
	v_mul_f32_e32 v129, v129, v212
	v_cvt_pk_bf16_f32 v190, v130, v129
	s_add_u32 s64, s64, 0x2000
	s_addc_u32 s65, s65, 0
	global_store_short v220, v190, s[64:65] offset:-4096
	global_store_short_d16_hi v220, v190, s[64:65] offset:-3072
	s_waitcnt lgkmcnt(12)
	v_fma_f32 v130, v130, v213, v183
	v_mul_f32_e32 v129, v129, v213
	v_cvt_pk_bf16_f32 v191, v130, v129
	global_store_short v220, v191, s[64:65] offset:-2048
	global_store_short_d16_hi v220, v191, s[64:65] offset:-1024
	s_waitcnt lgkmcnt(10)
	v_fma_f32 v130, v130, v214, v184
	v_mul_f32_e32 v129, v129, v214
	v_cvt_pk_bf16_f32 v190, v130, v129
	global_store_short v220, v190, s[64:65] offset:0
	global_store_short_d16_hi v220, v190, s[64:65] offset:1024
	s_waitcnt lgkmcnt(8)
	v_fma_f32 v130, v130, v215, v185
	v_mul_f32_e32 v129, v129, v215
	v_cvt_pk_bf16_f32 v191, v130, v129
	global_store_short v220, v191, s[64:65] offset:2048
	global_store_short_d16_hi v220, v191, s[64:65] offset:3072
	s_waitcnt lgkmcnt(6)
	v_fma_f32 v130, v130, v216, v186
	v_mul_f32_e32 v129, v129, v216
	v_cvt_pk_bf16_f32 v190, v130, v129
	s_add_u32 s64, s64, 0x2000
	s_addc_u32 s65, s65, 0
	global_store_short v220, v190, s[64:65] offset:-4096
	global_store_short_d16_hi v220, v190, s[64:65] offset:-3072
	s_waitcnt lgkmcnt(4)
	v_fma_f32 v130, v130, v217, v187
	v_mul_f32_e32 v129, v129, v217
	v_cvt_pk_bf16_f32 v191, v130, v129
	global_store_short v220, v191, s[64:65] offset:-2048
	global_store_short_d16_hi v220, v191, s[64:65] offset:-1024
	s_waitcnt lgkmcnt(2)
	v_fma_f32 v130, v130, v218, v188
	v_mul_f32_e32 v129, v129, v218
	v_cvt_pk_bf16_f32 v190, v130, v129
	global_store_short v220, v190, s[64:65] offset:0
	global_store_short_d16_hi v220, v190, s[64:65] offset:1024
	s_waitcnt lgkmcnt(0)
	v_fma_f32 v130, v130, v219, v189
	v_mul_f32_e32 v129, v129, v219
	v_cvt_pk_bf16_f32 v191, v130, v129
	global_store_short v220, v191, s[64:65] offset:2048
	global_store_short_d16_hi v220, v191, s[64:65] offset:3072
	s_add_u32 s0, s0, 0x8000
	s_addc_u32 s1, s1, 0
	v_add_u32_e32 v150, 0x4100, v150
	v_add_u32_e32 v151, 0x4100, v151
	s_cmp_lg_u32 s0, 0x20000
	s_cbranch_scc1 .Llru0_loop
	v_add_u32_e32 v156, 0x1000, v155
	v_add_u32_e32 v157, 0x1200, v155
	v_add_u32_e32 v158, 0x400, v155
	v_add_u32_e32 v159, 0x1400, v155
	v_add_u32_e32 v160, 0x1600, v155
	v_add_u32_e32 v161, 0x800, v155
	v_add_u32_e32 v162, 0x1800, v155
	v_add_u32_e32 v163, 0x1a00, v155
	v_add_u32_e32 v164, 0xc00, v155
	v_add_u32_e32 v165, 0x1c00, v155
	v_add_u32_e32 v166, 0x1e00, v155
	s_ashr_i32 s5, s4, 31
	s_lshl_b64 s[0:1], s[4:5], 9
	v_lshl_add_u64 v[0:1], s[0:1], 0, v[124:125]
	v_or_b32_e32 v0, v0, v126
	v_readlane_b32 s0, v254, 11
	v_lshlrev_b64 v[0:1], 2, v[0:1]
	v_readlane_b32 s1, v254, 12
	v_lshlrev_b32_e32 v6, 1, v121
	v_mov_b32_e32 v7, v177
	v_lshl_add_u64 v[2:3], s[0:1], 0, v[0:1]
	v_readlane_b32 s0, v254, 13
	v_readlane_b32 s1, v254, 14
	v_lshlrev_b32_e32 v8, 1, v133
	v_mov_b32_e32 v9, v177
	v_lshl_add_u64 v[6:7], v[114:115], 0, v[6:7]
	v_lshl_add_u64 v[0:1], s[0:1], 0, v[0:1]
	v_lshl_add_u64 v[6:7], v[6:7], 0, v[8:9]
	s_mov_b64 s[0:1], 0x20000
	v_lshl_add_u64 v[80:81], v[6:7], 0, s[0:1]
	s_mov_b64 s[0:1], 0x30000
	global_store_dword v[0:1], v130, off
	v_lshl_add_u64 v[0:1], s[22:23], 0, v[112:113]
	v_lshl_add_u64 v[78:79], v[6:7], 0, s[0:1]
	v_mov_b32_e32 v121, v177
	s_mov_b32 s0, 0x20000
	v_lshl_add_u64 v[76:77], v[0:1], 0, v[120:121]
	v_add_co_u32_e32 v0, vcc, s0, v6
	v_lshl_add_u64 v[4:5], s[38:39], 0, v[112:113]
	s_nop 0
	v_addc_co_u32_e32 v1, vcc, 0, v7, vcc
	v_lshl_add_u64 v[92:93], v[4:5], 0, v[120:121]
	v_add_co_u32_e32 v4, vcc, 0x30000, v6
	global_store_dword v[2:3], v129, off
	v_lshl_add_u64 v[2:3], s[26:27], 0, v[112:113]
	v_addc_co_u32_e32 v5, vcc, 0, v7, vcc
	v_lshl_add_u64 v[88:89], v[2:3], 0, v[120:121]
	v_readlane_b32 s0, v255, 0
	v_readlane_b32 s1, v255, 1
	v_readlane_b32 s30, v254, 47
	v_readlane_b32 s31, v254, 48
	s_add_u32 s0, s0, 0x4000
	s_addc_u32 s1, s1, 0
	s_sub_u32 s0, s0, s30
	s_subb_u32 s1, s1, s31
	v_lshl_add_u64 v[76:77], v[76:77], 0, s[0:1]
	global_load_dwordx4 v[192:195], v[76:77], off
	global_load_dwordx4 v[196:199], v[76:77], off offset:64
	global_load_dwordx4 v[200:203], v[76:77], off offset:128
	global_load_dwordx4 v[204:207], v[76:77], off offset:192
	s_nop 0
	global_load_dwordx4 v[0:3], v[0:1], off
	s_nop 0
	global_load_dwordx4 v[4:7], v[4:5], off
	s_nop 0
	global_load_dwordx4 v[8:11], v[80:81], off offset:64
	global_load_dwordx4 v[12:15], v[78:79], off offset:64
	global_load_dwordx4 v[16:19], v[88:89], off
	global_load_dwordx4 v[20:23], v[92:93], off
	s_waitcnt vmcnt(6)
; #define LAS __attribute__((address_space(3)))
; __device__ __forceinline__ float bf2f(bf16_t b) { return __uint_as_float(((unsigned)b) << 16); }
; template <int DIR> __device__ __forceinline__ void lru_dir(const Params& p, int l, int n, int h, int lane, LAS bf16_t* XC, LAS float* STA, LAS float* STU) {
;     ...
;         const f32x4 lam4 = *(const f32x4*)(lam + 16 * nf + 4 * q); ba4[nf] = *(const f32x4*)(b_a + 16 * nf + 4 * q); bx4[nf] = *(const f32x4*)(b_x + 16 * nf + 4 * q);
; #pragma unroll
;         for (int r = 0; r < 4; ++r) { const float e = __expf(-lam4[r]); const float l1p = e < 0.05f ? e * (1.0f - e * (0.5f - e * (0.33333334f - e * 0.25f))) : __logf(1.0f + e); sp4[nf][r] = -8.0f * l1p; }
;     }
;     float hcar = 0.f, P = 1.f;
; #pragma unroll 1
;     for (int g = 0; g < 4; ++g) {
;         const int mi = DIR == 0 ? g : 3 - g;
;         bf16_t hfp[16];
;         if (DIR == 1) {
; #pragma unroll
;             for (int s = 0; s < 16; ++s) hfp[s] = y[(size_t)(t0 + 16 * mi + s) * D + 64 * h + j];
;         }
;         bf16x8 xf[2];
; #pragma unroll
;         for (int ks = 0; ks < 2; ++ks) xf[ks] = *(const LAS bf16x8*)(XC + (16 * mi + c) * 520 + 64 * h + 32 * ks + 8 * q);
;         f32x4 za[4], zx[4];
; #pragma unroll
;         for (int nf = 0; nf < 4; ++nf) { za[nf] = (f32x4){0.f, 0.f, 0.f, 0.f}; zx[nf] = za[nf];
;             za[nf] = mfma16(wa[nf][0], xf[0], za[nf]); za[nf] = mfma16(wa[nf][1], xf[1], za[nf]);
;             zx[nf] = mfma16(wx[nf][0], xf[0], zx[nf]); zx[nf] = mfma16(wx[nf][1], xf[1], zx[nf]); }
; #pragma unroll
;         for (int nf = 0; nf < 4; ++nf) {
;             const int jo = 16 * nf + 4 * q;
;             const bf16x4 xc4 = *(const LAS bf16x4*)(XC + (16 * mi + c) * 520 + 64 * h + jo);
;             const f32x4 zav = za[nf] + ba4[nf], zxv = zx[nf] + bx4[nf];
;             f32x4 av, uv;
; #pragma unroll
;             for (int r = 0; r < 4; ++r) {
;                 const float ra = sigmoidf_(zav[r]), ix = sigmoidf_(zxv[r]);
;                 const float la = ra * sp4[nf][r];
;                 av[r] = __expf(la);
;                 const float x2 = 2.0f * la;
;                 const float om = -x2 * (1.0f + x2 * (0.5f + x2 * (0.16666667f + x2 * (0.041666668f + x2 * (0.0083333338f + x2 * (0.0013888889f + x2 * 0.0001984127f))))));
;                 uv[r] = bf2f((bf16_t)xc4[r]) * ix * __builtin_amdgcn_sqrtf(fmaxf(om, 0.f));
	v_mov_b32_e32 v100, v192
	v_mov_b32_e32 v101, v193
	v_mov_b32_e32 v102, v194
	v_mov_b32_e32 v103, v195
	global_load_dwordx4 v[24:27], v[80:81], off offset:2048
	global_load_dwordx4 v[28:31], v[80:81], off offset:2112
	global_load_dwordx4 v[32:35], v[78:79], off offset:2048
	global_load_dwordx4 v[36:39], v[78:79], off offset:2112
	global_load_dwordx4 v[40:43], v[88:89], off offset:64
	global_load_dwordx4 v[44:47], v[92:93], off offset:64
	v_mov_b32_e32 v104, v196
	v_mov_b32_e32 v105, v197
	v_mov_b32_e32 v106, v198
	v_mov_b32_e32 v107, v199
	v_add_co_u32_e32 v52, vcc, 0x1000, v80
	s_nop 1
	v_addc_co_u32_e32 v53, vcc, 0, v81, vcc
	v_add_co_u32_e32 v60, vcc, 0x1000, v78
	s_nop 1
	v_addc_co_u32_e32 v61, vcc, 0, v79, vcc
	global_load_dwordx4 v[48:51], v[52:53], off
	s_nop 0
	global_load_dwordx4 v[52:55], v[52:53], off offset:64
	s_nop 0
	global_load_dwordx4 v[56:59], v[60:61], off
	s_nop 0
	global_load_dwordx4 v[60:63], v[60:61], off offset:64
	s_nop 0
	global_load_dwordx4 v[64:67], v[88:89], off offset:128
	global_load_dwordx4 v[68:71], v[92:93], off offset:128
	v_mov_b32_e32 v108, v200
	v_mov_b32_e32 v109, v201
	v_mov_b32_e32 v110, v202
	v_mov_b32_e32 v111, v203
	v_add_co_u32_e32 v80, vcc, 0x1000, v80
	s_nop 1
	v_addc_co_u32_e32 v81, vcc, 0, v81, vcc
	v_add_co_u32_e32 v84, vcc, 0x1000, v78
	s_nop 1
	v_addc_co_u32_e32 v85, vcc, 0, v79, vcc
	global_load_dwordx4 v[72:75], v[80:81], off offset:2048
	s_nop 0
	global_load_dwordx4 v[76:79], v[80:81], off offset:2112
	s_nop 0
	global_load_dwordx4 v[80:83], v[84:85], off offset:2048
	s_nop 0
	global_load_dwordx4 v[84:87], v[84:85], off offset:2112
	s_nop 0
	global_load_dwordx4 v[88:91], v[88:89], off offset:192
	s_nop 0
	global_load_dwordx4 v[92:95], v[92:93], off offset:192
	s_waitcnt vmcnt(6)
	v_mov_b32_e32 v96, v204
	v_mov_b32_e32 v97, v205
	v_mov_b32_e32 v98, v206
	v_mov_b32_e32 v99, v207
	s_lshl_b64 s[0:1], s[28:29], 10
	s_add_u32 s0, s56, s0
	v_mul_f32_e32 v169, 0xc138aa3b, v96
	v_lshl_add_u32 v96, v124, 1, 0
	s_addc_u32 s1, s57, s1
	v_mul_f32_e32 v167, 0xc138aa3b, v98
	v_mul_f32_e32 v168, 0xc138aa3b, v97
	v_mul_f32_e32 v170, 0xc138aa3b, v111
	v_mul_f32_e32 v171, 0xc138aa3b, v110
	v_mul_f32_e32 v172, 0xc138aa3b, v109
	v_mul_f32_e32 v173, 0xc138aa3b, v108
	v_mul_f32_e32 v174, 0xc138aa3b, v107
	v_mul_f32_e32 v175, 0xc138aa3b, v106
	v_mul_f32_e32 v182, 0xc138aa3b, v105
	v_mul_f32_e32 v183, 0xc138aa3b, v104
	v_mul_f32_e32 v184, 0xc138aa3b, v103
	v_mul_f32_e32 v185, 0xc138aa3b, v102
	v_mul_f32_e32 v186, 0xc138aa3b, v101
	v_mul_f32_e32 v187, 0xc138aa3b, v100
	v_lshl_add_u32 v188, v133, 1, v96
	v_mul_f32_e32 v190, 0xc138aa3b, v99
	v_lshl_add_u32 v191, v132, 1, v96
	v_lshl_add_u64 v[128:129], s[0:1], 0, v[118:119]
	v_lshl_add_u64 v[130:131], s[56:57], 0, v[116:117]
	v_mov_b32_e32 v135, 1.0
	v_mov_b32_e32 v132, 0
	s_mov_b32 s0, 48
	v_mul_f32_e32 v16, 0xbfb8aa3b, v16
	v_mul_f32_e32 v17, 0xbfb8aa3b, v17
	v_mul_f32_e32 v18, 0xbfb8aa3b, v18
	v_mul_f32_e32 v19, 0xbfb8aa3b, v19
	v_mul_f32_e32 v20, 0xbfb8aa3b, v20
	v_mul_f32_e32 v21, 0xbfb8aa3b, v21
	v_mul_f32_e32 v22, 0xbfb8aa3b, v22
	v_mul_f32_e32 v23, 0xbfb8aa3b, v23
	v_mul_f32_e32 v40, 0xbfb8aa3b, v40
	v_mul_f32_e32 v41, 0xbfb8aa3b, v41
	v_mul_f32_e32 v42, 0xbfb8aa3b, v42
	v_mul_f32_e32 v43, 0xbfb8aa3b, v43
	v_mul_f32_e32 v44, 0xbfb8aa3b, v44
	v_mul_f32_e32 v45, 0xbfb8aa3b, v45
	v_mul_f32_e32 v46, 0xbfb8aa3b, v46
	v_mul_f32_e32 v47, 0xbfb8aa3b, v47
	v_mul_f32_e32 v64, 0xbfb8aa3b, v64
	v_mul_f32_e32 v65, 0xbfb8aa3b, v65
	v_mul_f32_e32 v66, 0xbfb8aa3b, v66
	v_mul_f32_e32 v67, 0xbfb8aa3b, v67
	v_mul_f32_e32 v68, 0xbfb8aa3b, v68
	v_mul_f32_e32 v69, 0xbfb8aa3b, v69
	v_mul_f32_e32 v70, 0xbfb8aa3b, v70
	v_mul_f32_e32 v71, 0xbfb8aa3b, v71
.LBB0_323:
	v_add_u32_e32 v133, s0, v127
	v_mad_u32_u24 v100, v133, s7, v188
	ds_read_b128 v[96:99], v100
	ds_read_b128 v[120:123], v100 offset:64
	v_mad_u32_u24 v133, v133, s7, v191
	ds_read_b64 v[146:147], v133
	v_lshl_add_u64 v[136:137], v[130:131], 0, v[176:177]
	s_waitcnt lgkmcnt(2)
	v_mfma_f32_16x16x32_bf16 v[100:103], v[0:3], v[96:99], 0
	s_mov_b32 s1, 0x1877000
	v_add_co_u32_e32 v150, vcc, s1, v136
	s_waitcnt lgkmcnt(1)
	v_mfma_f32_16x16x32_bf16 v[138:141], v[8:11], v[120:123], v[100:103]
	s_waitcnt lgkmcnt(0)
	v_and_b32_e32 v149, 0xffff0000, v147
	v_lshlrev_b32_e32 v148, 16, v147
	v_addc_co_u32_e32 v151, vcc, 0, v137, vcc
	v_mfma_f32_16x16x32_bf16 v[100:103], v[4:7], v[96:99], 0
	s_mov_b32 s1, 0x1876000
	v_and_b32_e32 v147, 0xffff0000, v146
	v_lshlrev_b32_e32 v146, 16, v146
	v_mfma_f32_16x16x32_bf16 v[142:145], v[12:15], v[120:123], v[100:103]
	global_load_ushort v189, v[150:151], off offset:2048
	global_load_ushort v204, v[150:151], off
	s_movk_i32 s28, 0xc000
	s_mov_b32 s29, -1
	v_mfma_f32_16x16x32_bf16 v[100:103], v[24:27], v[96:99], 0
	s_add_i32 s0, s0, -16
	s_cmp_lg_u32 s0, -16
	v_mfma_f32_16x16x32_bf16 v[116:119], v[28:31], v[120:123], v[100:103]
	v_mfma_f32_16x16x32_bf16 v[100:103], v[32:35], v[96:99], 0
	v_mfma_f32_16x16x32_bf16 v[112:115], v[36:39], v[120:123], v[100:103]
	s_nop 5
	v_fmamk_f32 v116, v116, 0xbfb8aa3b, v40
	v_exp_f32_e32 v116, v116
	v_mfma_f32_16x16x32_bf16 v[100:103], v[48:51], v[96:99], 0
	v_add_f32_e32 v116, 1.0, v116
	v_mfma_f32_16x16x32_bf16 v[108:111], v[52:55], v[120:123], v[100:103]
	v_fmamk_f32 v112, v112, 0xbfb8aa3b, v44
	v_exp_f32_e32 v112, v112
	v_fmamk_f32 v117, v117, 0xbfb8aa3b, v41
	v_mfma_f32_16x16x32_bf16 v[100:103], v[56:59], v[96:99], 0
	v_exp_f32_e32 v117, v117
	v_add_f32_e32 v112, 1.0, v112
	v_mfma_f32_16x16x32_bf16 v[104:107], v[60:63], v[120:123], v[100:103]
	v_add_f32_e32 v117, 1.0, v117
	v_fmamk_f32 v113, v113, 0xbfb8aa3b, v45
	v_exp_f32_e32 v113, v113
	s_waitcnt vmcnt(7)
; #define LAS __attribute__((address_space(3)))
; __device__ __forceinline__ float bf2f(bf16_t b) { return __uint_as_float(((unsigned)b) << 16); }
; __device__ __forceinline__ float sigmoidf_(float x) { return __builtin_amdgcn_rcpf(1.0f + __expf(-x)); }
; __device__ __forceinline__ f32x4 mfma16(bf16x8 a, bf16x8 b, f32x4 c) { return __builtin_amdgcn_mfma_f32_16x16x32_bf16(a, b, c, 0, 0, 0); }
; template <int DIR> __device__ __forceinline__ void lru_dir(const Params& p, int l, int n, int h, int lane, LAS bf16_t* XC, LAS float* STA, LAS float* STU) {
;     ...
;         for (int nf = 0; nf < 4; ++nf) { za[nf] = (f32x4){0.f, 0.f, 0.f, 0.f}; zx[nf] = za[nf];
;             za[nf] = mfma16(wa[nf][0], xf[0], za[nf]); za[nf] = mfma16(wa[nf][1], xf[1], za[nf]);
;             zx[nf] = mfma16(wx[nf][0], xf[0], zx[nf]); zx[nf] = mfma16(wx[nf][1], xf[1], zx[nf]); }
; #pragma unroll
;         for (int nf = 0; nf < 4; ++nf) {
;             const int jo = 16 * nf + 4 * q;
;             const bf16x4 xc4 = *(const LAS bf16x4*)(XC + (16 * mi + c) * 520 + 64 * h + jo);
;             const f32x4 zav = za[nf] + ba4[nf], zxv = zx[nf] + bx4[nf];
;             f32x4 av, uv;
; #pragma unroll
;             for (int r = 0; r < 4; ++r) {
;                 const float ra = sigmoidf_(zav[r]), ix = sigmoidf_(zxv[r]);
;                 const float la = ra * sp4[nf][r];
;                 av[r] = __expf(la);
;                 const float x2 = 2.0f * la;
;                 const float om = -x2 * (1.0f + x2 * (0.5f + x2 * (0.16666667f + x2 * (0.041666668f + x2 * (0.0083333338f + x2 * (0.0013888889f + x2 * 0.0001984127f))))));
;                 uv[r] = bf2f((bf16_t)xc4[r]) * ix * __builtin_amdgcn_sqrtf(fmaxf(om, 0.f));
	v_mfma_f32_16x16x32_bf16 v[100:103], v[72:75], v[96:99], 0
	v_fmamk_f32 v118, v118, 0xbfb8aa3b, v42
	v_add_f32_e32 v113, 1.0, v113
	s_waitcnt vmcnt(5)
	v_mfma_f32_16x16x32_bf16 v[96:99], v[80:83], v[96:99], 0
	v_exp_f32_e32 v118, v118
	v_fmamk_f32 v114, v114, 0xbfb8aa3b, v46
	v_mfma_f32_16x16x32_bf16 v[100:103], v[76:79], v[120:123], v[100:103]
	v_add_f32_e32 v118, 1.0, v118
	v_exp_f32_e32 v114, v114
	s_waitcnt vmcnt(4)
	v_mfma_f32_16x16x32_bf16 v[96:99], v[84:87], v[120:123], v[96:99]
	v_fmamk_f32 v120, v138, 0xbfb8aa3b, v16
	v_exp_f32_e32 v120, v120
	v_fmamk_f32 v121, v142, 0xbfb8aa3b, v20
	v_exp_f32_e32 v121, v121
	v_add_f32_e32 v120, 1.0, v120
	v_rcp_f32_e32 v120, v120
	v_add_f32_e32 v114, 1.0, v114
	v_add_f32_e32 v121, 1.0, v121
	v_rcp_f32_e32 v138, v121
	v_mul_f32_e32 v121, v187, v120
	v_exp_f32_e32 v120, v121
	s_nop 0
	v_fma_f32 v121, -v120, v120, 1.0
	v_max_f32_e32 v121, 0, v121
	v_sqrt_f32_e32 v142, v121
	v_fmamk_f32 v121, v139, 0xbfb8aa3b, v17
	v_exp_f32_e32 v121, v121
	v_fmamk_f32 v122, v143, 0xbfb8aa3b, v21
	v_exp_f32_e32 v122, v122
	v_add_f32_e32 v121, 1.0, v121
	v_rcp_f32_e32 v121, v121
	v_add_f32_e32 v122, 1.0, v122
	v_rcp_f32_e32 v139, v122
	v_mul_f32_e32 v122, v186, v121
	v_exp_f32_e32 v121, v122
	s_nop 0
	v_fma_f32 v122, -v121, v121, 1.0
	v_max_f32_e32 v122, 0, v122
	v_sqrt_f32_e32 v143, v122
	v_fmamk_f32 v122, v140, 0xbfb8aa3b, v18
	v_exp_f32_e32 v122, v122
	v_fmamk_f32 v123, v144, 0xbfb8aa3b, v22
	v_exp_f32_e32 v123, v123
	v_add_f32_e32 v122, 1.0, v122
	v_rcp_f32_e32 v122, v122
	v_pk_mul_f32 v[138:139], v[138:139], v[146:147]
	v_add_f32_e32 v123, 1.0, v123
	v_rcp_f32_e32 v140, v123
	v_mul_f32_e32 v123, v185, v122
	v_exp_f32_e32 v122, v123
	s_nop 0
	v_fma_f32 v123, -v122, v122, 1.0
	v_max_f32_e32 v123, 0, v123
	v_sqrt_f32_e32 v144, v123
	v_fmamk_f32 v123, v141, 0xbfb8aa3b, v19
	v_exp_f32_e32 v123, v123
	v_fmamk_f32 v134, v145, 0xbfb8aa3b, v23
	v_exp_f32_e32 v134, v134
	v_add_f32_e32 v123, 1.0, v123
	v_rcp_f32_e32 v123, v123
	v_pk_mul_f32 v[206:207], v[138:139], v[142:143]
	v_add_f32_e32 v134, 1.0, v134
	v_rcp_f32_e32 v141, v134
	v_mul_f32_e32 v134, v184, v123
	v_exp_f32_e32 v123, v134
	s_nop 0
	v_fma_f32 v134, -v123, v123, 1.0
	v_max_f32_e32 v134, 0, v134
	v_sqrt_f32_e32 v145, v134
	v_pk_mul_f32 v[140:141], v[140:141], v[148:149]
	v_add_co_u32_e32 v148, vcc, s1, v136
	s_mov_b32 s1, 0x1875000
	s_nop 0
	v_addc_co_u32_e32 v149, vcc, 0, v137, vcc
	v_add_co_u32_e32 v146, vcc, s1, v136
	s_mov_b32 s1, 0x1874000
	s_nop 0
	v_addc_co_u32_e32 v147, vcc, 0, v137, vcc
	v_pk_mul_f32 v[208:209], v[140:141], v[144:145]
	v_add_co_u32_e32 v144, vcc, s1, v136
	s_mov_b32 s1, 0x1873000
	s_nop 0
	v_addc_co_u32_e32 v145, vcc, 0, v137, vcc
	v_add_co_u32_e32 v142, vcc, s1, v136
	s_mov_b32 s1, 0x1872000
	s_nop 0
	v_addc_co_u32_e32 v143, vcc, 0, v137, vcc
	v_add_co_u32_e32 v140, vcc, s1, v136
	s_mov_b32 s1, 0x1871000
	s_nop 0
	v_addc_co_u32_e32 v141, vcc, 0, v137, vcc
	v_add_co_u32_e32 v138, vcc, s1, v136
	s_mov_b32 s1, 0x1870000
	s_nop 0
	v_addc_co_u32_e32 v139, vcc, 0, v137, vcc
	v_add_co_u32_e32 v136, vcc, s1, v136
	global_load_ushort v205, v[148:149], off offset:2048
	global_load_ushort v201, v[148:149], off
	v_addc_co_u32_e32 v137, vcc, 0, v137, vcc
	global_load_ushort v203, v[146:147], off offset:2048
	global_load_ushort v202, v[146:147], off
	global_load_ushort v193, v[144:145], off offset:2048
	global_load_ushort v134, v[144:145], off
	global_load_ushort v195, v[142:143], off offset:2048
	global_load_ushort v194, v[142:143], off
	global_load_ushort v197, v[140:141], off offset:2048
	global_load_ushort v196, v[140:141], off
	global_load_ushort v198, v[138:139], off offset:2048
	global_load_ushort v199, v[138:139], off
	global_load_ushort v200, v[136:137], off offset:2048
	global_load_ushort v192, v[136:137], off
	ds_write_b128 v154, v[120:123]
	ds_write_b128 v154, v[206:209] offset:4352
	v_rcp_f32_e32 v122, v116
	v_rcp_f32_e32 v116, v112
	v_fmamk_f32 v119, v119, 0xbfb8aa3b, v43
	v_exp_f32_e32 v119, v119
	v_mul_f32_e32 v122, v183, v122
	v_exp_f32_e32 v112, v122
	s_nop 0
	v_fma_f32 v122, -v112, v112, 1.0
	v_rcp_f32_e32 v123, v117
	v_rcp_f32_e32 v117, v113
	v_add_f32_e32 v119, 1.0, v119
	v_mul_f32_e32 v123, v182, v123
	v_exp_f32_e32 v113, v123
	s_nop 0
	v_fma_f32 v123, -v113, v113, 1.0
	v_rcp_f32_e32 v152, v118
	v_rcp_f32_e32 v118, v114
	v_fmamk_f32 v115, v115, 0xbfb8aa3b, v47
	v_exp_f32_e32 v115, v115
	v_mul_f32_e32 v152, v175, v152
	v_exp_f32_e32 v114, v152
	s_nop 0
	v_fma_f32 v152, -v114, v114, 1.0
	v_rcp_f32_e32 v153, v119
	v_add_f32_e32 v115, 1.0, v115
	v_rcp_f32_e32 v119, v115
	ds_read_b64 v[120:121], v133 offset:32
	v_mul_f32_e32 v153, v174, v153
	v_exp_f32_e32 v115, v153
	s_nop 0
	v_fma_f32 v153, -v115, v115, 1.0
	v_fmamk_f32 v108, v108, 0xbfb8aa3b, v64
	v_max_f32_e32 v122, 0, v122
	v_max_f32_e32 v123, 0, v123
	v_max_f32_e32 v152, 0, v152
	v_max_f32_e32 v153, 0, v153
	v_exp_f32_e32 v108, v108
	v_sqrt_f32_e32 v122, v122
	v_sqrt_f32_e32 v123, v123
	v_sqrt_f32_e32 v152, v152
	v_sqrt_f32_e32 v153, v153
	s_waitcnt lgkmcnt(0)
; #define LAS __attribute__((address_space(3)))
; __device__ __forceinline__ float bf2f(bf16_t b) { return __uint_as_float(((unsigned)b) << 16); }
; __device__ __forceinline__ float sigmoidf_(float x) { return __builtin_amdgcn_rcpf(1.0f + __expf(-x)); }
; __device__ __forceinline__ f32x4 mfma16(bf16x8 a, bf16x8 b, f32x4 c) { return __builtin_amdgcn_mfma_f32_16x16x32_bf16(a, b, c, 0, 0, 0); }
; template <int DIR> __device__ __forceinline__ void lru_dir(const Params& p, int l, int n, int h, int lane, LAS bf16_t* XC, LAS float* STA, LAS float* STU) {
;     ...
;         for (int nf = 0; nf < 4; ++nf) { za[nf] = (f32x4){0.f, 0.f, 0.f, 0.f}; zx[nf] = za[nf];
;             za[nf] = mfma16(wa[nf][0], xf[0], za[nf]); za[nf] = mfma16(wa[nf][1], xf[1], za[nf]);
;             zx[nf] = mfma16(wx[nf][0], xf[0], zx[nf]); zx[nf] = mfma16(wx[nf][1], xf[1], zx[nf]); }
; #pragma unroll
;         for (int nf = 0; nf < 4; ++nf) {
;             const int jo = 16 * nf + 4 * q;
;             const bf16x4 xc4 = *(const LAS bf16x4*)(XC + (16 * mi + c) * 520 + 64 * h + jo);
;             const f32x4 zav = za[nf] + ba4[nf], zxv = zx[nf] + bx4[nf];
;             f32x4 av, uv;
; #pragma unroll
;             for (int r = 0; r < 4; ++r) {
;                 const float ra = sigmoidf_(zav[r]), ix = sigmoidf_(zxv[r]);
;                 const float la = ra * sp4[nf][r];
;                 av[r] = __expf(la);
;                 const float x2 = 2.0f * la;
;                 const float om = -x2 * (1.0f + x2 * (0.5f + x2 * (0.16666667f + x2 * (0.041666668f + x2 * (0.0083333338f + x2 * (0.0013888889f + x2 * 0.0001984127f))))));
;                 uv[r] = bf2f((bf16_t)xc4[r]) * ix * __builtin_amdgcn_sqrtf(fmaxf(om, 0.f));
;             }
;             *(LAS f32x4*)(STA + c * 68 + jo) = av; *(LAS f32x4*)(STU + c * 68 + jo) = uv;
	v_and_b32_e32 v179, 0xffff0000, v120
	v_lshlrev_b32_e32 v178, 16, v120
	v_and_b32_e32 v181, 0xffff0000, v121
	v_lshlrev_b32_e32 v180, 16, v121
	v_pk_mul_f32 v[118:119], v[118:119], v[180:181]
	v_pk_mul_f32 v[116:117], v[116:117], v[178:179]
	v_add_f32_e32 v108, 1.0, v108
	v_fmamk_f32 v104, v104, 0xbfb8aa3b, v68
	v_pk_mul_f32 v[116:117], v[116:117], v[122:123]
	v_pk_mul_f32 v[118:119], v[118:119], v[152:153]
	ds_write_b128 v154, v[112:115] offset:64
	ds_write_b128 v154, v[116:119] offset:4416
	v_rcp_f32_e32 v114, v108
	v_exp_f32_e32 v104, v104
	v_fmamk_f32 v109, v109, 0xbfb8aa3b, v65
	v_mul_f32_e32 v114, v173, v114
	v_add_f32_e32 v104, 1.0, v104
	v_rcp_f32_e32 v108, v104
	v_exp_f32_e32 v104, v114
	v_exp_f32_e32 v109, v109
	s_nop 0
	v_add_f32_e32 v109, 1.0, v109
	v_fmamk_f32 v105, v105, 0xbfb8aa3b, v69
	v_fma_f32 v114, -v104, v104, 1.0
	v_rcp_f32_e32 v115, v109
	v_exp_f32_e32 v105, v105
	v_fmamk_f32 v110, v110, 0xbfb8aa3b, v66
	v_mul_f32_e32 v115, v172, v115
	v_add_f32_e32 v105, 1.0, v105
	v_rcp_f32_e32 v109, v105
	v_exp_f32_e32 v105, v115
	v_exp_f32_e32 v110, v110
	s_nop 0
	v_add_f32_e32 v110, 1.0, v110
	v_fmamk_f32 v106, v106, 0xbfb8aa3b, v70
	v_fma_f32 v115, -v105, v105, 1.0
	v_rcp_f32_e32 v116, v110
	v_exp_f32_e32 v106, v106
	v_fmamk_f32 v111, v111, 0xbfb8aa3b, v67
	v_mul_f32_e32 v116, v171, v116
	v_add_f32_e32 v106, 1.0, v106
	v_rcp_f32_e32 v110, v106
	v_exp_f32_e32 v106, v116
	v_exp_f32_e32 v111, v111
	s_nop 0
	v_add_f32_e32 v111, 1.0, v111
	v_fmamk_f32 v107, v107, 0xbfb8aa3b, v71
	v_fma_f32 v116, -v106, v106, 1.0
	v_rcp_f32_e32 v117, v111
	v_exp_f32_e32 v107, v107
	ds_read_b64 v[112:113], v133 offset:64
	s_waitcnt vmcnt(17)
	v_add_f32_e32 v100, v88, v100
	v_mul_f32_e32 v117, v170, v117
	v_add_f32_e32 v107, 1.0, v107
	v_rcp_f32_e32 v111, v107
	v_exp_f32_e32 v107, v117
	s_nop 0
	v_fma_f32 v117, -v107, v107, 1.0
	v_mul_f32_e32 v100, 0xbfb8aa3b, v100
	v_max_f32_e32 v114, 0, v114
	v_max_f32_e32 v115, 0, v115
	v_max_f32_e32 v116, 0, v116
	v_max_f32_e32 v117, 0, v117
	v_exp_f32_e32 v100, v100
	v_sqrt_f32_e32 v114, v114
	v_sqrt_f32_e32 v115, v115
	v_sqrt_f32_e32 v116, v116
	v_sqrt_f32_e32 v117, v117
	s_waitcnt lgkmcnt(0)
	v_and_b32_e32 v119, 0xffff0000, v112
	v_lshlrev_b32_e32 v118, 16, v112
	v_and_b32_e32 v121, 0xffff0000, v113
	v_lshlrev_b32_e32 v120, 16, v113
	s_waitcnt vmcnt(16)
	v_add_f32_e32 v96, v92, v96
	v_pk_mul_f32 v[110:111], v[110:111], v[120:121]
	v_pk_mul_f32 v[108:109], v[108:109], v[118:119]
	v_add_f32_e32 v100, 1.0, v100
	v_mul_f32_e32 v96, 0xbfb8aa3b, v96
	v_pk_mul_f32 v[108:109], v[108:109], v[114:115]
	v_pk_mul_f32 v[110:111], v[110:111], v[116:117]
	ds_write_b128 v154, v[104:107] offset:128
	ds_write_b128 v154, v[108:111] offset:4480
	v_rcp_f32_e32 v106, v100
	v_exp_f32_e32 v96, v96
	v_add_f32_e32 v101, v89, v101
	v_mul_f32_e32 v101, 0xbfb8aa3b, v101
	v_mul_f32_e32 v106, v169, v106
	v_add_f32_e32 v96, 1.0, v96
	v_rcp_f32_e32 v100, v96
	v_exp_f32_e32 v96, v106
	v_exp_f32_e32 v101, v101
	v_add_f32_e32 v97, v93, v97
	v_add_f32_e32 v101, 1.0, v101
	v_mul_f32_e32 v97, 0xbfb8aa3b, v97
	v_fma_f32 v106, -v96, v96, 1.0
	v_rcp_f32_e32 v107, v101
	v_exp_f32_e32 v97, v97
	v_add_f32_e32 v102, v90, v102
	v_mul_f32_e32 v102, 0xbfb8aa3b, v102
	v_mul_f32_e32 v107, v168, v107
	v_add_f32_e32 v97, 1.0, v97
	v_rcp_f32_e32 v101, v97
	v_exp_f32_e32 v97, v107
	v_exp_f32_e32 v102, v102
	v_add_f32_e32 v98, v94, v98
	v_add_f32_e32 v102, 1.0, v102
	v_mul_f32_e32 v98, 0xbfb8aa3b, v98
	v_fma_f32 v107, -v97, v97, 1.0
	v_rcp_f32_e32 v108, v102
	v_exp_f32_e32 v98, v98
	v_add_f32_e32 v103, v91, v103
	v_mul_f32_e32 v103, 0xbfb8aa3b, v103
	v_mul_f32_e32 v108, v167, v108
	v_add_f32_e32 v98, 1.0, v98
	v_rcp_f32_e32 v102, v98
	v_exp_f32_e32 v98, v108
	v_exp_f32_e32 v103, v103
	v_add_f32_e32 v99, v95, v99
	v_add_f32_e32 v103, 1.0, v103
	v_mul_f32_e32 v99, 0xbfb8aa3b, v99
	v_fma_f32 v108, -v98, v98, 1.0
	v_rcp_f32_e32 v109, v103
	v_exp_f32_e32 v99, v99
	ds_read_b64 v[104:105], v133 offset:96
	v_max_f32_e32 v106, 0, v106
	v_mul_f32_e32 v109, v190, v109
	v_add_f32_e32 v99, 1.0, v99
	v_rcp_f32_e32 v103, v99
	v_exp_f32_e32 v99, v109
	s_nop 0
	v_fma_f32 v109, -v99, v99, 1.0
	v_max_f32_e32 v107, 0, v107
	v_max_f32_e32 v108, 0, v108
	v_max_f32_e32 v109, 0, v109
	v_sqrt_f32_e32 v106, v106
	v_sqrt_f32_e32 v107, v107
	v_sqrt_f32_e32 v108, v108
	v_sqrt_f32_e32 v109, v109
	s_waitcnt lgkmcnt(0)
	v_and_b32_e32 v111, 0xffff0000, v104
	v_lshlrev_b32_e32 v110, 16, v104
	v_and_b32_e32 v113, 0xffff0000, v105
	v_lshlrev_b32_e32 v112, 16, v105
	v_pk_mul_f32 v[102:103], v[102:103], v[112:113]
	v_pk_mul_f32 v[100:101], v[100:101], v[110:111]
	v_pk_mul_f32 v[102:103], v[102:103], v[108:109]
	v_pk_mul_f32 v[100:101], v[100:101], v[106:107]
	ds_write_b128 v154, v[96:99] offset:192
	ds_write_b128 v154, v[100:103] offset:4544
	s_waitcnt lgkmcnt(0)
	ds_read2_b32 v[152:153], v164 offset0:184 offset1:252
	ds_read2_b32 v[122:123], v166 offset0:120 offset1:188
	s_waitcnt vmcnt(14)
	v_lshlrev_b32_e32 v180, 16, v204
	s_mov_b32 s1, 0xd3e7000
	s_waitcnt lgkmcnt(1)
	v_mov_b32_e32 v211, v152
	s_waitcnt lgkmcnt(0)
	v_fma_f32 v178, v132, v153, v123
	ds_read2_b32 v[98:99], v155 offset1:68
	ds_read2_b32 v[96:97], v156 offset0:64 offset1:132
	ds_read2_b32 v[100:101], v155 offset0:136 offset1:204
	ds_read2_b32 v[102:103], v157 offset0:72 offset1:140
	ds_read2_b32 v[104:105], v158 offset0:16 offset1:84
	ds_read2_b32 v[108:109], v159 offset0:80 offset1:148
	ds_read2_b32 v[106:107], v158 offset0:152 offset1:220
	ds_read2_b32 v[112:113], v160 offset0:88 offset1:156
	ds_read2_b32 v[110:111], v161 offset0:32 offset1:100
	ds_read2_b32 v[114:115], v162 offset0:96 offset1:164
	ds_read2_b32 v[116:117], v161 offset0:168 offset1:236
	ds_read2_b32 v[118:119], v163 offset0:104 offset1:172
	ds_read2_b32 v[120:121], v164 offset0:48 offset1:116
	ds_read2_b32 v[132:133], v165 offset0:112 offset1:180
	v_fmac_f32_e32 v122, v152, v178
	v_mov_b32_e32 v123, v135
	v_lshlrev_b32_e32 v135, 16, v189
	v_add_f32_e32 v181, v122, v180
	s_waitcnt vmcnt(13)
; __device__ __forceinline__ float bf2f(bf16_t b) { return __uint_as_float(((unsigned)b) << 16); }
; __device__ __forceinline__ unsigned cvtpk(float lo, float hi) { const f32x2 v = (f32x2){lo, hi}; const bf16v2 b = __builtin_convertvector(v, bf16v2); return __builtin_bit_cast(unsigned, b); }
; #define LDS_FENCE() asm volatile("s_waitcnt lgkmcnt(0)" ::: "memory")
; template <int DIR> __device__ __forceinline__ void lru_dir(const Params& p, int l, int n, int h, int lane, LAS bf16_t* XC, LAS float* STA, LAS float* STU) {
;     ...
;         for (int s = 0; s < 16; ++s) { aa[s] = STA[s * 68 + j]; uu[s] = STU[s * 68 + j]; }
;         LDS_FENCE();
; #pragma unroll
;         for (int s = 0; s < 16; ++s) {
;             const int tl = DIR == 0 ? s : 15 - s;
;             hcar = aa[tl] * hcar + uu[tl]; P *= aa[tl];
;             const size_t row = (size_t)(t0 + 16 * mi + tl);
;             if (DIR == 0) { const unsigned w = cvtpk(hcar, P); y[row * D + 64 * h + j] = (bf16_t)(w & 0xffffu); y[row * D + 512 + 64 * h + j] = (bf16_t)(w >> 16); }
;             else { const unsigned w = cvtpk(bf2f(hfp[tl]) + hcar, P); y[row * D + 64 * h + j] = (bf16_t)(w & 0xffffu); __builtin_nontemporal_store((bf16_t)(w >> 16), PB + row * 512 + 64 * h + j); }
;         }
	v_lshlrev_b32_e32 v180, 16, v205
	s_waitcnt lgkmcnt(1)
	v_mov_b32_e32 v204, v121
	v_mov_b32_e32 v205, v153
	v_add_f32_e32 v135, v178, v135
	v_lshl_add_u64 v[178:179], v[128:129], 0, v[176:177]
	v_pk_mul_f32 v[206:207], v[204:205], v[122:123]
	s_waitcnt lgkmcnt(0)
	v_mov_b32_e32 v210, v133
	v_add_co_u32_e32 v208, vcc, s1, v178
	v_pk_mul_f32 v[152:153], v[210:211], v[206:207]
	v_cvt_pk_bf16_f32 v135, v135, v207
	v_addc_co_u32_e32 v209, vcc, 0, v179, vcc
	v_pk_fma_f32 v[122:123], v[204:205], v[122:123], v[210:211]
	v_cvt_pk_bf16_f32 v133, v181, v153
	v_mov_b32_e32 v181, v121
	s_waitcnt lgkmcnt(0)
	global_store_short v[150:151], v135, off offset:2048
	global_store_short_d16_hi v[208:209], v135, off offset:3072 nt
	global_store_short v[150:151], v133, off
	global_store_short_d16_hi v[208:209], v133, off offset:2048 nt
	v_pk_add_f32 v[150:151], v[122:123], v[180:181]
	v_pk_mul_f32 v[152:153], v[152:153], v[180:181]
	v_fmac_f32_e32 v132, v120, v122
	v_cvt_pk_bf16_f32 v121, v150, v153
	global_store_short v[148:149], v121, off offset:2048
	global_store_short_d16_hi v[208:209], v121, off offset:1024 nt
	s_waitcnt vmcnt(18)
	v_lshlrev_b32_e32 v121, 16, v201
	v_fmac_f32_e32 v119, v117, v132
	v_add_f32_e32 v123, v132, v121
	s_waitcnt vmcnt(17)
	v_lshlrev_b32_e32 v121, 16, v203
	v_mov_b32_e32 v132, v116
	v_mov_b32_e32 v133, v120
	v_mov_b32_e32 v152, v119
	v_add_f32_e32 v135, v119, v121
	v_pk_mul_f32 v[120:121], v[132:133], v[152:153]
	s_mov_b32 s1, 0xd3e6000
	v_cvt_pk_bf16_f32 v119, v123, v121
	global_store_short v[148:149], v119, off
	global_store_short_d16_hi v[208:209], v119, off nt
	v_mov_b32_e32 v119, v117
	v_pk_fma_f32 v[132:133], v[132:133], v[152:153], v[118:119]
	v_pk_mul_f32 v[118:119], v[118:119], v[120:121]
	v_add_co_u32_e32 v120, vcc, s1, v178
	s_waitcnt vmcnt(18)
	v_lshlrev_b32_e32 v122, 16, v202
	v_mov_b32_e32 v118, v132
	v_cvt_pk_bf16_f32 v117, v135, v119
	v_addc_co_u32_e32 v121, vcc, 0, v179, vcc
	v_mov_b32_e32 v123, v116
	global_store_short v[146:147], v117, off offset:2048
	global_store_short_d16_hi v[120:121], v117, off offset:3072 nt
	v_pk_add_f32 v[116:117], v[132:133], v[122:123]
	v_pk_mul_f32 v[118:119], v[118:119], v[122:123]
	v_fma_f32 v115, v111, v132, v115
	v_cvt_pk_bf16_f32 v116, v116, v119
	global_store_short v[146:147], v116, off
	global_store_short_d16_hi v[120:121], v116, off offset:2048 nt
	s_waitcnt vmcnt(21)
	v_lshlrev_b32_e32 v116, 16, v193
	v_add_f32_e32 v116, v115, v116
	v_fmac_f32_e32 v114, v110, v115
	s_waitcnt vmcnt(20)
	v_lshlrev_b32_e32 v115, 16, v134
	v_add_f32_e32 v117, v114, v115
	v_fma_f32 v113, v107, v114, v113
	s_waitcnt vmcnt(19)
	v_lshlrev_b32_e32 v114, 16, v195
	v_add_f32_e32 v122, v113, v114
	v_fmac_f32_e32 v112, v106, v113
	s_waitcnt vmcnt(18)
	v_lshlrev_b32_e32 v113, 16, v194
	v_add_f32_e32 v123, v112, v113
	v_fmac_f32_e32 v109, v105, v112
	s_waitcnt vmcnt(17)
	v_lshlrev_b32_e32 v112, 16, v197
	v_add_f32_e32 v132, v109, v112
	v_mov_b32_e32 v112, v104
	v_mov_b32_e32 v113, v111
	v_mov_b32_e32 v118, v109
	v_pk_mul_f32 v[114:115], v[112:113], v[118:119]
	s_mov_b32 s1, 0xd3e5000
	v_cvt_pk_bf16_f32 v109, v116, v115
	global_store_short v[144:145], v109, off offset:2048
	global_store_short_d16_hi v[120:121], v109, off offset:1024 nt
	v_mov_b32_e32 v109, v110
	v_pk_fma_f32 v[110:111], v[112:113], v[118:119], v[108:109]
	v_pk_mul_f32 v[108:109], v[108:109], v[114:115]
	v_add_co_u32_e32 v114, vcc, s1, v178
	v_cvt_pk_bf16_f32 v108, v117, v109
	v_mov_b32_e32 v111, v109
	global_store_short v[144:145], v108, off
	global_store_short_d16_hi v[120:121], v108, off nt
	v_mov_b32_e32 v108, v101
	v_mov_b32_e32 v109, v107
	v_pk_mul_f32 v[112:113], v[108:109], v[110:111]
	v_addc_co_u32_e32 v115, vcc, 0, v179, vcc
	v_cvt_pk_bf16_f32 v107, v122, v113
	v_mov_b32_e32 v116, v103
	v_mov_b32_e32 v117, v106
	global_store_short v[142:143], v107, off offset:2048
	global_store_short_d16_hi v[114:115], v107, off offset:3072 nt
	v_pk_fma_f32 v[106:107], v[108:109], v[110:111], v[116:117]
	v_pk_mul_f32 v[108:109], v[116:117], v[112:113]
	s_waitcnt vmcnt(22)
	v_lshlrev_b32_e32 v133, 16, v196
	v_mov_b32_e32 v107, v109
	v_cvt_pk_bf16_f32 v103, v123, v109
	v_mov_b32_e32 v108, v100
	v_mov_b32_e32 v109, v105
	v_pk_mul_f32 v[112:113], v[108:109], v[106:107]
	global_store_short v[142:143], v103, off
	global_store_short_d16_hi v[114:115], v103, off offset:2048 nt
	v_cvt_pk_bf16_f32 v103, v132, v113
	global_store_short v[140:141], v103, off offset:2048
	global_store_short_d16_hi v[114:115], v103, off offset:1024 nt
	v_mov_b32_e32 v103, v104
	v_add_f32_e32 v110, v110, v133
	v_pk_fma_f32 v[104:105], v[108:109], v[106:107], v[102:103]
	v_pk_mul_f32 v[102:103], v[102:103], v[112:113]
	s_waitcnt vmcnt(25)
	v_lshlrev_b32_e32 v134, 16, v198
	v_cvt_pk_bf16_f32 v102, v110, v103
	v_mov_b32_e32 v105, v103
	global_store_short v[140:141], v102, off
	global_store_short_d16_hi v[114:115], v102, off nt
	v_mov_b32_e32 v102, v99
	v_mov_b32_e32 v103, v101
	v_add_f32_e32 v108, v106, v134
	v_pk_mul_f32 v[106:107], v[102:103], v[104:105]
	s_mov_b32 s1, 0xd3e4000
	v_cvt_pk_bf16_f32 v101, v108, v107
	v_add_co_u32_e32 v108, vcc, s1, v178
	s_waitcnt vmcnt(26)
	v_lshlrev_b32_e32 v135, 16, v199
	v_addc_co_u32_e32 v109, vcc, 0, v179, vcc
	v_mov_b32_e32 v110, v97
	v_mov_b32_e32 v111, v100
	global_store_short v[138:139], v101, off offset:2048
	global_store_short_d16_hi v[108:109], v101, off offset:3072 nt
	v_add_f32_e32 v112, v104, v135
	v_pk_fma_f32 v[100:101], v[102:103], v[104:105], v[110:111]
	v_pk_mul_f32 v[102:103], v[110:111], v[106:107]
	s_waitcnt vmcnt(27)
	v_lshlrev_b32_e32 v146, 16, v200
	v_mov_b32_e32 v101, v103
	v_cvt_pk_bf16_f32 v97, v112, v103
	global_store_short v[138:139], v97, off
	global_store_short_d16_hi v[108:109], v97, off offset:2048 nt
	v_add_f32_e32 v97, v100, v146
	v_pk_mul_f32 v[102:103], v[98:99], v[100:101]
	v_lshl_add_u64 v[128:129], v[128:129], 0, s[28:29]
	v_cvt_pk_bf16_f32 v97, v97, v103
	global_store_short v[136:137], v97, off offset:2048
	global_store_short_d16_hi v[108:109], v97, off offset:1024 nt
	v_mov_b32_e32 v97, v98
	v_pk_fma_f32 v[132:133], v[98:99], v[100:101], v[96:97]
	v_pk_mul_f32 v[134:135], v[96:97], v[102:103]
	s_waitcnt vmcnt(30)
	v_lshlrev_b32_e32 v96, 16, v192
	s_movk_i32 s28, 0x8000
	v_add_f32_e32 v96, v132, v96
	s_mov_b32 s29, -1
	v_cvt_pk_bf16_f32 v96, v96, v135
	v_lshl_add_u64 v[130:131], v[130:131], 0, s[28:29]
	global_store_short v[136:137], v96, off
	global_store_short_d16_hi v[108:109], v96, off nt
	s_cbranch_scc1 .LBB0_323
; __device__ __forceinline__ int obid() { int t = blockIdx.x; asm volatile("" : "+s"(t)); return t; }
; template <int DIR> __device__ __forceinline__ void lru_dir(const Params& p, int l, int n, int h, int lane, LAS bf16_t* XC, LAS float* STA, LAS float* STU) {
;     ...
;     Aprod[(size_t)(DIR * NCH + n) * 512 + 64 * h + j] = P; Hend[(size_t)(DIR * NCH + n) * 512 + 64 * h + j] = hcar;
; __global__ void __launch_bounds__(NTHR, 2) mk_fwd(Params p) {
;     ...
;         case 2: for (int n = obid(); n < NCH; n += gridDim.x) mixer_lru<0>(p, l, n, lds);
	s_lshl_b64 s[0:1], s[4:5], 9
	s_add_u32 s0, s0, 0x20000
	s_addc_u32 s1, s1, 0
	v_lshl_add_u64 v[0:1], s[0:1], 0, v[124:125]
	v_or_b32_e32 v0, v0, v126
	v_readlane_b32 s0, v254, 11
	v_lshlrev_b64 v[0:1], 2, v[0:1]
	v_readlane_b32 s1, v254, 12
	s_nop 1
	v_lshl_add_u64 v[2:3], s[0:1], 0, v[0:1]
	v_readlane_b32 s0, v254, 13
	v_readlane_b32 s1, v254, 14
	global_store_dword v[2:3], v135, off
	s_nop 0
	v_lshl_add_u64 v[0:1], s[0:1], 0, v[0:1]
	v_readlane_b32 s0, v255, 8
	v_readlane_b32 s1, v255, 9
	global_store_dword v[0:1], v132, off
	s_barrier
	s_load_dword s0, s[0:1], 0x0
	s_waitcnt lgkmcnt(0)
	s_add_i32 s4, s0, s4
	s_cmpk_gt_i32 s4, 0xff
	s_cbranch_scc0 .LBB0_192
